# plus removal of provably dead denormal-scaling/inf-check ops in GLA gate log-sigmoid (bitwise identical)
# speedup vs baseline: 1.0275x; 1.0059x over previous
.LBB0_96:
	v_mov_b32_e32 v125, v220
	s_lshl_b32 s4, s66, 4
	v_ashrrev_i32_e32 v2, 6, v125
	v_lshrrev_b32_e32 v0, 4, v125
	s_lshl_b32 s5, s66, 6
	s_ashr_i32 s67, s66, 31
	v_lshlrev_b32_e32 v64, 4, v2
	v_bfe_u32 v0, v0, 1, 1
	s_and_b32 s6, s5, 0x1fc0
	s_and_b32 s7, s4, 0xffffe000
	s_lshl_b64 s[4:5], s[66:67], 17
	v_readlane_b32 s2, v253, 8
	v_or_b32_e32 v0, v0, v64
	v_readlane_b32 s3, v253, 9
	s_add_u32 s4, s2, s4
	s_waitcnt lgkmcnt(0)
	v_ashrrev_i32_e32 v1, 31, v0
	v_and_b32_e32 v129, 15, v125
	s_addc_u32 s5, s3, s5
	v_lshlrev_b64 v[0:1], 9, v[0:1]
	v_lshl_add_u64 v[0:1], s[4:5], 0, v[0:1]
	v_lshlrev_b32_e32 v176, 5, v129
	v_lshl_add_u64 v[0:1], v[0:1], 0, v[176:177]
	v_and_b32_e32 v176, 16, v125
	s_bfe_u32 s8, s66, 0x20007
	s_waitcnt lgkmcnt(0)
	v_lshl_add_u64 v[130:131], v[0:1], 0, v[176:177]
	s_or_b32 s67, s7, s6
	s_lshl_b32 s92, s8, 8
	s_lshl_b32 s4, s8, 10
	v_readlane_b32 s2, v255, 44
	v_add_co_u32_e32 v0, vcc, s22, v130
	s_add_u32 s4, s2, s4
	v_readlane_b32 s2, v255, 45
	v_lshlrev_b32_e32 v126, 5, v2
	v_ashrrev_i32_e32 v112, 3, v125
	v_lshlrev_b32_e32 v40, 4, v125
	v_and_b32_e32 v120, 48, v64
	v_or_b32_e32 v124, s67, v129
	v_addc_co_u32_e32 v1, vcc, 0, v131, vcc
	s_addc_u32 s5, s2, 0
	v_ashrrev_i32_e32 v127, 31, v126
	v_and_b32_e32 v111, 0x70, v40
	v_add_u32_e32 v40, s67, v112
	v_mov_b64_e32 v[56:57], s[64:65]
	v_or_b32_e32 v58, v120, v124
	global_load_dwordx4 v[36:39], v[130:131], off
	global_load_dwordx4 v[32:35], v[130:131], off offset:1024
	global_load_dwordx4 v[28:31], v[130:131], off offset:2048
	global_load_dwordx4 v[24:27], v[130:131], off offset:3072
	global_load_dwordx4 v[20:23], v[0:1], off
	global_load_dwordx4 v[16:19], v[0:1], off offset:1024
	global_load_dwordx4 v[12:15], v[0:1], off offset:2048
	global_load_dwordx4 v[8:11], v[0:1], off offset:3072
	v_lshl_add_u64 v[0:1], v[126:127], 2, s[4:5]
	v_mad_i64_i32 v[40:41], s[4:5], v40, s96, v[56:57]
	v_mad_i64_i32 v[56:57], s[4:5], v58, s96, v[56:57]
	s_mov_b64 s[2:3], 0x2800
	v_lshl_add_u64 v[60:61], v[56:57], 0, s[2:3]
	v_readlane_b32 s2, v255, 46
	s_lshl_b32 s7, s8, 7
	v_and_b32_e32 v106, 0xffffffc0, v64
	v_readlane_b32 s3, v255, 47
	v_or_b32_e32 v64, s2, v129
	v_ashrrev_i32_e32 v107, 31, v106
	v_or_b32_e32 v64, s7, v64
	v_mov_b32_e32 v65, s3
	v_lshl_add_u64 v[64:65], v[64:65], 0, v[106:107]
	v_readlane_b32 s2, v253, 10
	v_lshlrev_b64 v[64:65], 6, v[64:65]
	v_readlane_b32 s3, v253, 11
	v_bfe_u32 v164, v125, 4, 2
	v_lshlrev_b32_e32 v176, 4, v164
	v_lshl_add_u64 v[64:65], s[2:3], 0, v[64:65]
	v_readlane_b32 s2, v255, 48
	s_or_b32 s4, s7, s2
	v_or_b32_e32 v66, s4, v129
	v_add_u32_e32 v66, v66, v106
	v_lshl_add_u64 v[64:65], v[64:65], 0, v[176:177]
	s_mov_b32 s2, 0x8000
	v_ashrrev_i32_e32 v67, 31, v66
	v_readlane_b32 s12, v254, 0
	v_lshl_add_u64 v[40:41], v[40:41], 0, s[92:93]
	v_lshlrev_b32_e32 v104, 1, v111
	v_mov_b32_e32 v105, v177
	v_xor_b32_e32 v62, 32, v176
	v_mov_b32_e32 v63, v177
	v_add_co_u32_e32 v68, vcc, s2, v64
	v_lshlrev_b64 v[66:67], 2, v[66:67]
	v_readlane_b32 s22, v254, 10
	v_readlane_b32 s23, v254, 11
	v_readlane_b32 s26, v254, 14
	v_readlane_b32 s27, v254, 15
	s_mul_i32 s5, s67, 0x2a00
	v_lshl_add_u64 v[0:1], v[0:1], 0, v[176:177]
	v_lshl_add_u64 v[48:49], v[40:41], 0, v[104:105]
	v_lshl_add_u64 v[56:57], v[60:61], 0, v[176:177]
	v_lshl_add_u64 v[60:61], v[60:61], 0, v[62:63]
	v_addc_co_u32_e32 v69, vcc, 0, v65, vcc
	v_lshl_add_u64 v[96:97], s[22:23], 0, v[66:67]
	v_lshl_add_u64 v[98:99], s[26:27], 0, v[66:67]
	s_mul_hi_i32 s4, s67, 0x2a00
	s_add_u32 s5, s64, s5
	global_load_dwordx4 v[4:7], v[0:1], off
	s_nop 0
	global_load_dwordx4 v[0:3], v[0:1], off offset:64
	s_nop 0
	global_load_dwordx4 v[44:47], v[48:49], off offset:16
	global_load_dwordx4 v[52:55], v[48:49], off
	global_load_dwordx4 v[40:43], v[48:49], off offset:1040
	s_nop 0
	global_load_dwordx4 v[48:51], v[48:49], off offset:1024
	s_addc_u32 s7, s65, s4
	global_load_dwordx4 v[56:59], v[56:57], off
	s_lshl_b32 s4, s8, 9
	global_load_dwordx4 v[60:63], v[60:61], off
	s_add_u32 s4, s5, s4
	global_load_dwordx4 v[88:91], v[64:65], off
	global_load_dwordx4 v[92:95], v[68:69], off
	global_load_dword v118, v[96:97], off
	global_load_dword v119, v[98:99], off
	global_load_dwordx4 v[80:83], v[64:65], off offset:1024
	global_load_dwordx4 v[84:87], v[68:69], off offset:1024
	global_load_dword v116, v[96:97], off offset:64
	global_load_dword v117, v[98:99], off offset:64
	global_load_dwordx4 v[72:75], v[64:65], off offset:2048
	global_load_dwordx4 v[76:79], v[68:69], off offset:2048
	global_load_dword v114, v[96:97], off offset:128
	global_load_dword v115, v[98:99], off offset:128
	s_nop 0
	global_load_dwordx4 v[64:67], v[64:65], off offset:3072
	s_nop 0
	global_load_dwordx4 v[68:71], v[68:69], off offset:3072
	s_nop 0
	global_load_dword v105, v[96:97], off offset:192
	global_load_dword v107, v[98:99], off offset:192
	v_mov_b32_e32 v98, v220
	s_addc_u32 s5, s7, 0
	v_lshlrev_b32_sdwa v96, v223, v98 dst_sel:DWORD dst_unused:UNUSED_PAD src0_sel:DWORD src1_sel:BYTE_0
	v_mov_b32_e32 v97, v177
	v_ashrrev_i32_e32 v98, 5, v98
	v_lshl_add_u64 v[108:109], s[4:5], 0, v[96:97]
	v_and_b32_e32 v121, -8, v98
	v_mad_i64_i32 v[96:97], s[4:5], v121, s96, v[108:109]
	global_load_ushort v100, v[96:97], off offset:2048
	v_or_b32_e32 v96, 1, v121
	v_mad_i64_i32 v[96:97], s[4:5], v96, s96, v[108:109]
	global_load_ushort v101, v[96:97], off offset:2048
	v_or_b32_e32 v96, 2, v121
	v_mad_i64_i32 v[96:97], s[4:5], v96, s96, v[108:109]
	global_load_ushort v102, v[96:97], off offset:2048
	v_or_b32_e32 v96, 3, v121
	v_mad_i64_i32 v[96:97], s[4:5], v96, s96, v[108:109]
	global_load_ushort v103, v[96:97], off offset:2048
	v_or_b32_e32 v96, 4, v121
	v_mad_i64_i32 v[96:97], s[4:5], v96, s96, v[108:109]
	global_load_ushort v122, v[96:97], off offset:2048
	v_or_b32_e32 v96, 5, v121
	v_mad_i64_i32 v[96:97], s[4:5], v96, s96, v[108:109]
	global_load_ushort v123, v[96:97], off offset:2048
	v_or_b32_e32 v96, 6, v121
	v_mad_i64_i32 v[96:97], s[4:5], v96, s96, v[108:109]
	global_load_ushort v99, v[96:97], off offset:2048
	v_or_b32_e32 v96, 7, v98
	v_mad_i64_i32 v[96:97], s[4:5], v96, s96, v[108:109]
	global_load_ushort v96, v[96:97], off offset:2048
	s_mov_b32 s7, 0x5040100
	s_waitcnt vmcnt(0)
	v_mfma_f32_16x16x32_bf16 v[88:91], v[56:59], v[88:91], 0
	v_readlane_b32 s15, v254, 3
	v_readlane_b32 s14, v254, 2
	s_movk_i32 s15, 0x90
	v_mfma_f32_16x16x32_bf16 v[92:95], v[60:63], v[92:95], 0
	s_add_i32 s14, 0, 0x12000
	s_nop 2
	v_add_f32_e32 v88, v118, v88
	s_mov_b32 s8, 0x3f317217
	v_lshlrev_b32_e32 v128, 2, v164
	v_add_f32_e32 v89, v118, v89
	v_add_f32_e32 v93, v119, v93
	v_add_f32_e32 v90, v118, v90
	v_mfma_f32_16x16x32_bf16 v[80:83], v[56:59], v[80:83], 0
	v_ashrrev_i32_e32 v113, 7, v125
	v_and_b32_e32 v110, 0x7f, v125
	v_lshlrev_b32_e32 v165, 3, v164
	v_mfma_f32_16x16x32_bf16 v[84:87], v[60:63], v[84:87], 0
	s_mov_b32 s6, 32
	s_nop 2
	v_add_f32_e32 v80, v116, v80
	v_add_f32_e32 v81, v116, v81
	v_mfma_f32_16x16x32_bf16 v[72:75], v[56:59], v[72:75], 0
	s_mov_b64 s[2:3], s[64:65]
	v_add_f32_e32 v84, v117, v84
	v_add_f32_e32 v85, v117, v85
	v_mfma_f32_16x16x32_bf16 v[76:79], v[60:63], v[76:79], 0
	v_readlane_b32 s13, v254, 1
	v_perm_b32 v97, v103, v102, s7
	s_nop 1
	v_add_f32_e32 v72, v114, v72
	v_add_f32_e32 v73, v114, v73
	v_mfma_f32_16x16x32_bf16 v[56:59], v[56:59], v[64:67], 0
	s_nop 0
	v_add_f32_e32 v76, v115, v76
	v_readlane_b32 s16, v254, 4
	v_readlane_b32 s17, v254, 5
	v_mfma_f32_16x16x32_bf16 v[60:63], v[60:63], v[68:71], 0
	v_perm_b32 v98, v123, v122, s7
	s_nop 1
	v_add_f32_e32 v56, v105, v56
	v_min_f32_e32 v64, 0, v56
	v_readlane_b32 s18, v254, 6
	v_readlane_b32 s19, v254, 7
	s_nop 0
	v_add_f32_e32 v60, v107, v60
	v_readlane_b32 s20, v254, 8
	v_readlane_b32 s21, v254, 9
	v_perm_b32 v99, v96, v99, s7
	v_perm_b32 v96, v101, v100, s7
	v_add_u32_e32 v100, 16, v121
	v_mad_i64_i32 v[100:101], s[4:5], v100, s96, v[108:109]
	global_load_ushort v122, v[100:101], off offset:2048
	v_add_u32_e32 v100, 17, v121
	v_mad_i64_i32 v[100:101], s[4:5], v100, s96, v[108:109]
	global_load_ushort v123, v[100:101], off offset:2048
	v_add_u32_e32 v100, 18, v121
	v_mad_i64_i32 v[100:101], s[4:5], v100, s96, v[108:109]
	global_load_ushort v132, v[100:101], off offset:2048
	v_add_u32_e32 v100, 19, v121
	v_mad_i64_i32 v[100:101], s[4:5], v100, s96, v[108:109]
	global_load_ushort v133, v[100:101], off offset:2048
	v_add_u32_e32 v100, 20, v121
	v_mad_i64_i32 v[100:101], s[4:5], v100, s96, v[108:109]
	global_load_ushort v102, v[100:101], off offset:2048
	v_add_u32_e32 v100, 21, v121
	v_mad_i64_i32 v[100:101], s[4:5], v100, s96, v[108:109]
	global_load_ushort v134, v[100:101], off offset:2048
	v_add_u32_e32 v100, 22, v121
	v_mad_i64_i32 v[100:101], s[4:5], v100, s96, v[108:109]
	global_load_ushort v103, v[100:101], off offset:2048
	v_add_u32_e32 v100, 23, v121
	v_mad_i64_i32 v[100:101], s[4:5], v100, s96, v[108:109]
	global_load_ushort v100, v[100:101], off offset:2048
	v_readlane_b32 s24, v254, 12
	v_readlane_b32 s25, v254, 13
	s_waitcnt vmcnt(4)
	v_perm_b32 v101, v133, v132, s7
	s_waitcnt vmcnt(2)
	v_perm_b32 v102, v134, v102, s7
	s_waitcnt vmcnt(0)
	v_perm_b32 v103, v100, v103, s7
	v_perm_b32 v100, v123, v122, s7
	v_add_u32_e32 v122, 32, v121
	v_mad_i64_i32 v[122:123], s[4:5], v122, s96, v[108:109]
	global_load_ushort v132, v[122:123], off offset:2048
	v_add_u32_e32 v122, 33, v121
	v_mad_i64_i32 v[122:123], s[4:5], v122, s96, v[108:109]
	global_load_ushort v136, v[122:123], off offset:2048
	v_add_u32_e32 v122, 34, v121
	v_mad_i64_i32 v[122:123], s[4:5], v122, s96, v[108:109]
	global_load_ushort v133, v[122:123], off offset:2048
	v_add_u32_e32 v122, 35, v121
	v_mad_i64_i32 v[122:123], s[4:5], v122, s96, v[108:109]
	global_load_ushort v137, v[122:123], off offset:2048
	v_add_u32_e32 v122, 36, v121
	v_mad_i64_i32 v[122:123], s[4:5], v122, s96, v[108:109]
	global_load_ushort v134, v[122:123], off offset:2048
	v_add_u32_e32 v122, 37, v121
	v_mad_i64_i32 v[122:123], s[4:5], v122, s96, v[108:109]
	global_load_ushort v138, v[122:123], off offset:2048
	v_add_u32_e32 v122, 38, v121
	v_mad_i64_i32 v[122:123], s[4:5], v122, s96, v[108:109]
	global_load_ushort v135, v[122:123], off offset:2048
	v_add_u32_e32 v122, 39, v121
	v_mad_i64_i32 v[122:123], s[4:5], v122, s96, v[108:109]
	global_load_ushort v122, v[122:123], off offset:2048
	s_waitcnt vmcnt(6)
	v_perm_b32 v132, v136, v132, s7
	s_waitcnt vmcnt(4)
	v_perm_b32 v133, v137, v133, s7
	s_waitcnt vmcnt(2)
	v_perm_b32 v134, v138, v134, s7
	s_waitcnt vmcnt(0)
	v_perm_b32 v135, v122, v135, s7
	v_add_u32_e32 v122, 48, v121
	v_mad_i64_i32 v[122:123], s[4:5], v122, s96, v[108:109]
	global_load_ushort v136, v[122:123], off offset:2048
	v_add_u32_e32 v122, 49, v121
	v_mad_i64_i32 v[122:123], s[4:5], v122, s96, v[108:109]
	global_load_ushort v140, v[122:123], off offset:2048
	v_add_u32_e32 v122, 50, v121
	v_mad_i64_i32 v[122:123], s[4:5], v122, s96, v[108:109]
	global_load_ushort v137, v[122:123], off offset:2048
	v_add_u32_e32 v122, 51, v121
	v_mad_i64_i32 v[122:123], s[4:5], v122, s96, v[108:109]
	global_load_ushort v141, v[122:123], off offset:2048
	v_add_u32_e32 v122, 52, v121
	v_mad_i64_i32 v[122:123], s[4:5], v122, s96, v[108:109]
	global_load_ushort v138, v[122:123], off offset:2048
	v_add_u32_e32 v122, 53, v121
	v_mad_i64_i32 v[122:123], s[4:5], v122, s96, v[108:109]
	global_load_ushort v142, v[122:123], off offset:2048
	v_add_u32_e32 v122, 54, v121
	v_add_u32_e32 v121, 55, v121
	v_mad_i64_i32 v[122:123], s[4:5], v122, s96, v[108:109]
	v_mad_i64_i32 v[108:109], s[4:5], v121, s96, v[108:109]
	global_load_ushort v122, v[122:123], off offset:2048
	s_waitcnt vmcnt(5)
	v_perm_b32 v136, v140, v136, s7
	global_load_ushort v108, v[108:109], off offset:2048
	s_barrier
	s_waitcnt vmcnt(4)
	v_perm_b32 v137, v141, v137, s7
	s_waitcnt vmcnt(2)
	v_perm_b32 v138, v142, v138, s7
	s_waitcnt vmcnt(0)
	v_perm_b32 v139, v108, v122, s7
	v_mov_b32_e32 v108, v220
	s_mov_b32 s7, 0xbfb8aa3b
	v_ashrrev_i32_e32 v109, 5, v108
	v_lshlrev_b32_e32 v109, 1, v109
	v_mul_u32_u24_sdwa v108, v108, s15 dst_sel:DWORD dst_unused:UNUSED_PAD src0_sel:BYTE_0 src1_sel:DWORD
	v_and_b32_e32 v109, -16, v109
	v_add3_u32 v108, s14, v108, v109
	ds_write_b128 v108, v[96:99]
	ds_write_b128 v108, v[100:103] offset:32
	ds_write_b128 v108, v[132:135] offset:64
	ds_write_b128 v108, v[136:139] offset:96
	v_add_f32_e32 v98, v119, v92
	v_min_f32_e32 v92, 0, v88
	v_mul_f32_e64 v88, |v88|, s7
	v_exp_f32_e32 v88, v88
	v_or_b32_e32 v96, v128, v120
	v_or_b32_e32 v97, v106, v129
	v_mul_f32_e64 v56, |v56|, s7
	v_add_f32_e32 v88, 1.0, v88
	v_exp_f32_e32 v56, v56
	s_nop 0
	v_log_f32_e32 v88, v88
	v_add_f32_e32 v56, 1.0, v56
	v_mul_f32_e32 v99, 0x3f317217, v88
	v_fma_f32 v99, v88, s8, -v99
	v_fmac_f32_e32 v99, 0x3377d1cf, v88
	v_fmac_f32_e32 v99, 0x3f317217, v88
	s_nop 1
	v_mov_b32_e32 v88, v99
	v_sub_f32_e32 v88, v92, v88
	v_mul_f32_e32 v92, 0x3d800000, v88
	v_lshl_add_u32 v88, v96, 7, v97
	v_mul_f32_e64 v97, |v98|, s7
	v_exp_f32_e32 v97, v97
	v_min_f32_e32 v96, 0, v98
	v_lshl_add_u32 v88, v88, 2, 0
	v_add_f32_e32 v97, 1.0, v97
	s_nop 1
	v_log_f32_e32 v97, v97
	s_nop 0
	v_mul_f32_e32 v98, 0x3f317217, v97
	v_fma_f32 v98, v97, s8, -v98
	v_fmac_f32_e32 v98, 0x3377d1cf, v97
	v_fmac_f32_e32 v98, 0x3f317217, v97
	s_nop 1
	v_mov_b32_e32 v97, v98
	v_sub_f32_e32 v96, v96, v97
	v_min_f32_e32 v97, 0, v89
	v_mul_f32_e64 v89, |v89|, s7
	v_exp_f32_e32 v89, v89
	v_mul_f32_e32 v96, 0x3d800000, v96
	v_add_f32_e32 v89, 1.0, v89
	s_nop 1
	v_log_f32_e32 v89, v89
	s_nop 0
	v_mul_f32_e32 v98, 0x3f317217, v89
	v_fma_f32 v98, v89, s8, -v98
	v_fmac_f32_e32 v98, 0x3377d1cf, v89
	v_fmac_f32_e32 v98, 0x3f317217, v89
	s_nop 1
	v_mov_b32_e32 v89, v98
	v_sub_f32_e32 v89, v97, v89
	v_min_f32_e32 v97, 0, v93
	v_mul_f32_e64 v93, |v93|, s7
	v_exp_f32_e32 v93, v93
	v_mul_f32_e32 v89, 0x3d800000, v89
	v_add_f32_e32 v93, 1.0, v93
	s_nop 1
	v_log_f32_e32 v93, v93
	s_nop 0
	v_mul_f32_e32 v98, 0x3f317217, v93
	v_fma_f32 v98, v93, s8, -v98
	v_fmac_f32_e32 v98, 0x3377d1cf, v93
	v_fmac_f32_e32 v98, 0x3f317217, v93
	s_nop 1
	v_mov_b32_e32 v93, v98
	v_sub_f32_e32 v93, v97, v93
	v_mul_f32_e32 v93, 0x3d800000, v93
	ds_write_b32 v88, v93 offset:41472
	v_add_f32_e32 v93, v119, v94
	v_min_f32_e32 v94, 0, v90
	v_mul_f32_e64 v90, |v90|, s7
	v_exp_f32_e32 v90, v90
	s_nop 0
	v_add_f32_e32 v90, 1.0, v90
	s_nop 1
	v_log_f32_e32 v90, v90
	s_nop 0
	v_mul_f32_e32 v97, 0x3f317217, v90
	v_fma_f32 v97, v90, s8, -v97
	v_fmac_f32_e32 v97, 0x3377d1cf, v90
	v_fmac_f32_e32 v97, 0x3f317217, v90
	s_nop 1
	v_mov_b32_e32 v90, v97
	v_sub_f32_e32 v90, v94, v90
	v_mul_f32_e32 v90, 0x3d800000, v90
	ds_write_b32 v88, v90 offset:9216
	v_min_f32_e32 v90, 0, v93
	v_mul_f32_e64 v93, |v93|, s7
	v_exp_f32_e32 v93, v93
	s_nop 0
	v_add_f32_e32 v93, 1.0, v93
	s_nop 1
	v_log_f32_e32 v93, v93
	s_nop 0
	v_mul_f32_e32 v94, 0x3f317217, v93
	v_fma_f32 v94, v93, s8, -v94
	v_fmac_f32_e32 v94, 0x3377d1cf, v93
	v_fmac_f32_e32 v94, 0x3f317217, v93
	s_nop 1
	v_mov_b32_e32 v93, v94
	v_sub_f32_e32 v90, v90, v93
	v_mul_f32_e32 v90, 0x3d800000, v90
	ds_write_b32 v88, v90 offset:41984
	v_add_f32_e32 v90, v118, v91
	v_min_f32_e32 v93, 0, v90
	v_mul_f32_e64 v90, |v90|, s7
	v_exp_f32_e32 v90, v90
	v_add_f32_e32 v91, v119, v95
	v_add_f32_e32 v90, 1.0, v90
	s_nop 1
	v_log_f32_e32 v90, v90
	s_nop 0
	v_mul_f32_e32 v94, 0x3f317217, v90
	v_fma_f32 v94, v90, s8, -v94
	v_fmac_f32_e32 v94, 0x3377d1cf, v90
	v_fmac_f32_e32 v94, 0x3f317217, v90
	s_nop 1
	v_mov_b32_e32 v90, v94
	v_sub_f32_e32 v90, v93, v90
	v_mul_f32_e32 v90, 0x3d800000, v90
	ds_write_b32 v88, v90 offset:9728
	v_min_f32_e32 v90, 0, v91
	v_mul_f32_e64 v91, |v91|, s7
	v_exp_f32_e32 v91, v91
	s_nop 0
	v_add_f32_e32 v91, 1.0, v91
	s_nop 1
	v_log_f32_e32 v91, v91
	s_nop 0
	v_mul_f32_e32 v93, 0x3f317217, v91
	v_fma_f32 v93, v91, s8, -v93
	v_fmac_f32_e32 v93, 0x3377d1cf, v91
	v_fmac_f32_e32 v93, 0x3f317217, v91
	s_nop 1
	v_mov_b32_e32 v91, v93
	v_sub_f32_e32 v90, v90, v91
	v_mul_f32_e32 v90, 0x3d800000, v90
	ds_write_b32 v88, v90 offset:42496
	v_min_f32_e32 v90, 0, v80
	v_mul_f32_e64 v80, |v80|, s7
	v_exp_f32_e32 v80, v80
	s_nop 0
	v_add_f32_e32 v80, 1.0, v80
	s_nop 1
	v_log_f32_e32 v80, v80
	s_nop 0
	v_mul_f32_e32 v91, 0x3f317217, v80
	v_fma_f32 v91, v80, s8, -v91
	v_fmac_f32_e32 v91, 0x3377d1cf, v80
	v_fmac_f32_e32 v91, 0x3f317217, v80
	s_nop 1
	v_mov_b32_e32 v80, v91
	v_sub_f32_e32 v80, v90, v80
	v_mul_f32_e32 v90, 0x3d800000, v80
	v_add_u32_e32 v80, 0x2000, v88
	ds_write2_b32 v80, v92, v90 offset1:16
	v_min_f32_e32 v90, 0, v84
	v_mul_f32_e64 v84, |v84|, s7
	v_exp_f32_e32 v84, v84
	s_nop 0
	v_add_f32_e32 v84, 1.0, v84
	s_nop 1
	v_log_f32_e32 v84, v84
	s_nop 0
	v_mul_f32_e32 v91, 0x3f317217, v84
	v_fma_f32 v91, v84, s8, -v91
	v_fmac_f32_e32 v91, 0x3377d1cf, v84
	v_fmac_f32_e32 v91, 0x3f317217, v84
	s_nop 1
	v_mov_b32_e32 v84, v91
	v_sub_f32_e32 v84, v90, v84
	v_mul_f32_e32 v90, 0x3d800000, v84
	v_add_u32_e32 v84, 0xa000, v88
	ds_write2_b32 v84, v96, v90 offset1:16
	v_min_f32_e32 v90, 0, v81
	v_mul_f32_e64 v81, |v81|, s7
	v_exp_f32_e32 v81, v81
	s_nop 0
	v_add_f32_e32 v81, 1.0, v81
	s_nop 1
	v_log_f32_e32 v81, v81
	s_nop 0
	v_mul_f32_e32 v91, 0x3f317217, v81
	v_fma_f32 v91, v81, s8, -v91
	v_fmac_f32_e32 v91, 0x3377d1cf, v81
	v_fmac_f32_e32 v91, 0x3f317217, v81
	s_nop 1
	v_mov_b32_e32 v81, v91
	v_sub_f32_e32 v81, v90, v81
	v_mul_f32_e32 v81, 0x3d800000, v81
	ds_write2_b32 v80, v89, v81 offset0:128 offset1:144
	v_min_f32_e32 v81, 0, v85
	v_mul_f32_e64 v85, |v85|, s7
	v_exp_f32_e32 v85, v85
	s_nop 0
	v_add_f32_e32 v85, 1.0, v85
	s_nop 1
	v_log_f32_e32 v85, v85
	s_nop 0
	v_mul_f32_e32 v89, 0x3f317217, v85
	v_fma_f32 v89, v85, s8, -v89
	v_fmac_f32_e32 v89, 0x3377d1cf, v85
	v_fmac_f32_e32 v89, 0x3f317217, v85
	s_nop 1
	v_mov_b32_e32 v85, v89
	v_sub_f32_e32 v81, v81, v85
	v_mul_f32_e32 v85, 0x3d800000, v81
	v_add_f32_e32 v81, v116, v82
	v_add_f32_e32 v82, v117, v86
	v_min_f32_e32 v86, 0, v81
	v_mul_f32_e64 v81, |v81|, s7
	v_exp_f32_e32 v81, v81
	s_nop 0
	v_add_f32_e32 v81, 1.0, v81
	s_nop 1
	v_log_f32_e32 v81, v81
	s_nop 0
	v_mul_f32_e32 v89, 0x3f317217, v81
	v_fma_f32 v89, v81, s8, -v89
	v_fmac_f32_e32 v89, 0x3377d1cf, v81
	v_fmac_f32_e32 v89, 0x3f317217, v81
	s_nop 1
	v_mov_b32_e32 v81, v89
	v_sub_f32_e32 v81, v86, v81
	v_min_f32_e32 v86, 0, v82
	v_mul_f32_e64 v82, |v82|, s7
	v_exp_f32_e32 v82, v82
	v_mul_f32_e32 v81, 0x3d800000, v81
	v_add_f32_e32 v82, 1.0, v82
	s_nop 1
	v_log_f32_e32 v82, v82
	s_nop 0
	v_mul_f32_e32 v89, 0x3f317217, v82
	v_fma_f32 v89, v82, s8, -v89
	v_fmac_f32_e32 v89, 0x3377d1cf, v82
	v_fmac_f32_e32 v89, 0x3f317217, v82
	s_nop 1
	v_mov_b32_e32 v82, v89
	v_sub_f32_e32 v82, v86, v82
	v_mul_f32_e32 v82, 0x3d800000, v82
	ds_write_b32 v88, v82 offset:42048
	v_add_f32_e32 v82, v116, v83
	v_min_f32_e32 v86, 0, v82
	v_mul_f32_e64 v82, |v82|, s7
	v_exp_f32_e32 v82, v82
	v_add_f32_e32 v83, v117, v87
	v_add_f32_e32 v82, 1.0, v82
	s_nop 1
	v_log_f32_e32 v82, v82
	s_nop 0
	v_mul_f32_e32 v87, 0x3f317217, v82
	v_fma_f32 v87, v82, s8, -v87
	v_fmac_f32_e32 v87, 0x3377d1cf, v82
	v_fmac_f32_e32 v87, 0x3f317217, v82
	s_nop 1
	v_mov_b32_e32 v82, v87
	v_sub_f32_e32 v82, v86, v82
	v_mul_f32_e32 v82, 0x3d800000, v82
	ds_write_b32 v88, v82 offset:9792
	v_min_f32_e32 v82, 0, v83
	v_mul_f32_e64 v83, |v83|, s7
	v_exp_f32_e32 v83, v83
	s_nop 0
	v_add_f32_e32 v83, 1.0, v83
	s_nop 1
	v_log_f32_e32 v83, v83
	s_nop 0
	v_mul_f32_e32 v86, 0x3f317217, v83
	v_fma_f32 v86, v83, s8, -v86
	v_fmac_f32_e32 v86, 0x3377d1cf, v83
	v_fmac_f32_e32 v86, 0x3f317217, v83
	s_nop 1
	v_mov_b32_e32 v83, v86
	v_sub_f32_e32 v82, v82, v83
	v_mul_f32_e32 v82, 0x3d800000, v82
	ds_write_b32 v88, v82 offset:42560
	v_min_f32_e32 v82, 0, v72
	v_mul_f32_e64 v72, |v72|, s7
	v_exp_f32_e32 v72, v72
	s_nop 0
	v_add_f32_e32 v72, 1.0, v72
	s_nop 1
	v_log_f32_e32 v72, v72
	s_nop 0
	v_mul_f32_e32 v83, 0x3f317217, v72
	v_fma_f32 v83, v72, s8, -v83
	v_fmac_f32_e32 v83, 0x3377d1cf, v72
	v_fmac_f32_e32 v83, 0x3f317217, v72
	s_nop 1
	v_mov_b32_e32 v72, v83
	v_sub_f32_e32 v72, v82, v72
	v_min_f32_e32 v82, 0, v76
	v_mul_f32_e64 v76, |v76|, s7
	v_exp_f32_e32 v76, v76
	v_mul_f32_e32 v72, 0x3d800000, v72
	v_add_f32_e32 v76, 1.0, v76
	s_nop 1
	v_log_f32_e32 v76, v76
	s_nop 0
	v_mul_f32_e32 v83, 0x3f317217, v76
	v_fma_f32 v83, v76, s8, -v83
	v_fmac_f32_e32 v83, 0x3377d1cf, v76
	v_fmac_f32_e32 v83, 0x3f317217, v76
	s_nop 1
	v_mov_b32_e32 v76, v83
	v_sub_f32_e32 v76, v82, v76
	v_mul_f32_e32 v76, 0x3d800000, v76
	ds_write_b32 v88, v76 offset:41088
	v_add_f32_e32 v76, v115, v77
	v_min_f32_e32 v77, 0, v73
	v_mul_f32_e64 v73, |v73|, s7
	v_exp_f32_e32 v73, v73
	s_nop 0
	v_add_f32_e32 v73, 1.0, v73
	s_nop 1
	v_log_f32_e32 v73, v73
	s_nop 0
	v_mul_f32_e32 v82, 0x3f317217, v73
	v_fma_f32 v82, v73, s8, -v82
	v_fmac_f32_e32 v82, 0x3377d1cf, v73
	v_fmac_f32_e32 v82, 0x3f317217, v73
	s_nop 1
	v_mov_b32_e32 v73, v82
	v_sub_f32_e32 v73, v77, v73
	v_mul_f32_e32 v73, 0x3d800000, v73
	ds_write_b32 v88, v73 offset:8832
	v_min_f32_e32 v73, 0, v76
	v_mul_f32_e64 v76, |v76|, s7
	v_exp_f32_e32 v76, v76
	s_nop 0
	v_add_f32_e32 v76, 1.0, v76
	s_nop 1
	v_log_f32_e32 v76, v76
	s_nop 0
	v_mul_f32_e32 v77, 0x3f317217, v76
	v_fma_f32 v77, v76, s8, -v77
	v_fmac_f32_e32 v77, 0x3377d1cf, v76
	v_fmac_f32_e32 v77, 0x3f317217, v76
	s_nop 1
	v_mov_b32_e32 v76, v77
	v_sub_f32_e32 v73, v73, v76
	v_mul_f32_e32 v73, 0x3d800000, v73
	ds_write2_b32 v84, v85, v73 offset0:144 offset1:160
	v_add_f32_e32 v73, v114, v74
	v_min_f32_e32 v76, 0, v73
	v_mul_f32_e64 v73, |v73|, s7
	v_exp_f32_e32 v73, v73
	v_add_f32_e32 v74, v115, v78
	v_add_f32_e32 v73, 1.0, v73
	s_nop 1
	v_log_f32_e32 v73, v73
	s_nop 0
	v_mul_f32_e32 v77, 0x3f317217, v73
	v_fma_f32 v77, v73, s8, -v77
	v_fmac_f32_e32 v77, 0x3377d1cf, v73
	v_fmac_f32_e32 v77, 0x3f317217, v73
	s_nop 1
	v_mov_b32_e32 v73, v77
	v_sub_f32_e32 v73, v76, v73
	v_mul_f32_e32 v73, 0x3d800000, v73
	v_add_u32_e32 v76, 0x2400, v88
	ds_write2_b32 v76, v81, v73 offset0:16 offset1:32
	v_min_f32_e32 v73, 0, v74
	v_mul_f32_e64 v74, |v74|, s7
	v_exp_f32_e32 v74, v74
	s_nop 0
	v_add_f32_e32 v74, 1.0, v74
	s_nop 1
	v_log_f32_e32 v74, v74
	s_nop 0
	v_mul_f32_e32 v76, 0x3f317217, v74
	v_fma_f32 v76, v74, s8, -v76
	v_fmac_f32_e32 v76, 0x3377d1cf, v74
	v_fmac_f32_e32 v76, 0x3f317217, v74
	s_nop 1
	v_mov_b32_e32 v74, v76
	v_sub_f32_e32 v73, v73, v74
	v_mul_f32_e32 v73, 0x3d800000, v73
	ds_write_b32 v88, v73 offset:42112
	v_add_f32_e32 v73, v114, v75
	v_min_f32_e32 v75, 0, v73
	v_mul_f32_e64 v73, |v73|, s7
	v_exp_f32_e32 v73, v73
	v_add_f32_e32 v74, v115, v79
	v_add_f32_e32 v73, 1.0, v73
	s_nop 1
	v_log_f32_e32 v73, v73
	s_nop 0
	v_mul_f32_e32 v76, 0x3f317217, v73
	v_fma_f32 v76, v73, s8, -v76
	v_fmac_f32_e32 v76, 0x3377d1cf, v73
	v_fmac_f32_e32 v76, 0x3f317217, v73
	s_nop 1
	v_mov_b32_e32 v73, v76
	v_sub_f32_e32 v73, v75, v73
	v_mul_f32_e32 v73, 0x3d800000, v73
	ds_write_b32 v88, v73 offset:9856
	v_min_f32_e32 v73, 0, v74
	v_mul_f32_e64 v74, |v74|, s7
	v_exp_f32_e32 v74, v74
	s_nop 0
	v_add_f32_e32 v74, 1.0, v74
	s_nop 1
	v_log_f32_e32 v74, v74
	s_nop 0
	v_mul_f32_e32 v75, 0x3f317217, v74
	v_fma_f32 v75, v74, s8, -v75
	v_fmac_f32_e32 v75, 0x3377d1cf, v74
	v_fmac_f32_e32 v75, 0x3f317217, v74
	s_nop 1
	v_mov_b32_e32 v74, v75
	v_sub_f32_e32 v73, v73, v74
	v_log_f32_e32 v56, v56
	v_mul_f32_e32 v73, 0x3d800000, v73
	ds_write_b32 v88, v73 offset:42624
	v_mul_f32_e32 v65, 0x3f317217, v56
	v_fma_f32 v65, v56, s8, -v65
	v_fmac_f32_e32 v65, 0x3377d1cf, v56
	v_fmac_f32_e32 v65, 0x3f317217, v56
	s_nop 1
	v_mov_b32_e32 v56, v65
	v_sub_f32_e32 v56, v64, v56
	v_mul_f32_e32 v56, 0x3d800000, v56
	ds_write2_b32 v80, v72, v56 offset0:32 offset1:48
	v_min_f32_e32 v56, 0, v60
	v_mul_f32_e64 v60, |v60|, s7
	v_exp_f32_e32 v60, v60
	s_nop 0
	v_add_f32_e32 v60, 1.0, v60
	s_nop 1
	v_log_f32_e32 v60, v60
	s_nop 0
	v_mul_f32_e32 v64, 0x3f317217, v60
	v_fma_f32 v64, v60, s8, -v64
	v_fmac_f32_e32 v64, 0x3377d1cf, v60
	v_fmac_f32_e32 v64, 0x3f317217, v60
	s_nop 1
	v_mov_b32_e32 v60, v64
	v_sub_f32_e32 v56, v56, v60
	v_mul_f32_e32 v56, 0x3d800000, v56
	ds_write_b32 v88, v56 offset:41152
	v_add_f32_e32 v56, v105, v57
	v_min_f32_e32 v60, 0, v56
	v_mul_f32_e64 v56, |v56|, s7
	v_exp_f32_e32 v56, v56
	v_add_f32_e32 v57, v107, v61
	v_add_f32_e32 v56, 1.0, v56
	s_nop 1
	v_log_f32_e32 v56, v56
	s_nop 0
	v_mul_f32_e32 v61, 0x3f317217, v56
	v_fma_f32 v61, v56, s8, -v61
	v_fmac_f32_e32 v61, 0x3377d1cf, v56
	v_fmac_f32_e32 v61, 0x3f317217, v56
	s_nop 1
	v_mov_b32_e32 v56, v61
	v_sub_f32_e32 v56, v60, v56
	v_mul_f32_e32 v56, 0x3d800000, v56
	ds_write_b32 v88, v56 offset:8896
	v_min_f32_e32 v56, 0, v57
	v_mul_f32_e64 v57, |v57|, s7
	v_exp_f32_e32 v57, v57
	s_nop 0
	v_add_f32_e32 v57, 1.0, v57
	s_nop 1
	v_log_f32_e32 v57, v57
	s_nop 0
	v_mul_f32_e32 v60, 0x3f317217, v57
	v_fma_f32 v60, v57, s8, -v60
	v_fmac_f32_e32 v60, 0x3377d1cf, v57
	v_fmac_f32_e32 v60, 0x3f317217, v57
	s_nop 1
	v_mov_b32_e32 v57, v60
	v_sub_f32_e32 v56, v56, v57
	v_mul_f32_e32 v56, 0x3d800000, v56
	ds_write_b32 v88, v56 offset:41664
	v_add_f32_e32 v56, v105, v58
	v_min_f32_e32 v58, 0, v56
	v_mul_f32_e64 v56, |v56|, s7
	v_exp_f32_e32 v56, v56
	v_add_f32_e32 v57, v107, v62
	v_add_f32_e32 v56, 1.0, v56
	s_nop 1
	v_log_f32_e32 v56, v56
	s_nop 0
	v_mul_f32_e32 v60, 0x3f317217, v56
	v_fma_f32 v60, v56, s8, -v60
	v_fmac_f32_e32 v60, 0x3377d1cf, v56
	v_fmac_f32_e32 v60, 0x3f317217, v56
	s_nop 1
	v_mov_b32_e32 v56, v60
	v_sub_f32_e32 v56, v58, v56
	v_mul_f32_e32 v56, 0x3d800000, v56
	ds_write_b32 v88, v56 offset:9408
	v_min_f32_e32 v56, 0, v57
	v_mul_f32_e64 v57, |v57|, s7
	v_exp_f32_e32 v57, v57
	s_nop 0
	v_add_f32_e32 v57, 1.0, v57
	s_nop 1
	v_log_f32_e32 v57, v57
	s_nop 0
	v_mul_f32_e32 v58, 0x3f317217, v57
	v_fma_f32 v58, v57, s8, -v58
	v_fmac_f32_e32 v58, 0x3377d1cf, v57
	v_fmac_f32_e32 v58, 0x3f317217, v57
	s_nop 1
	v_mov_b32_e32 v57, v58
	v_sub_f32_e32 v56, v56, v57
	v_mul_f32_e32 v56, 0x3d800000, v56
	ds_write_b32 v88, v56 offset:42176
	v_add_f32_e32 v56, v105, v59
	v_min_f32_e32 v58, 0, v56
	v_mul_f32_e64 v56, |v56|, s7
	v_exp_f32_e32 v56, v56
	v_add_f32_e32 v57, v107, v63
	v_add_f32_e32 v56, 1.0, v56
	s_nop 1
	v_log_f32_e32 v56, v56
	s_nop 0
	v_mul_f32_e32 v59, 0x3f317217, v56
	v_fma_f32 v59, v56, s8, -v59
	v_fmac_f32_e32 v59, 0x3377d1cf, v56
	v_fmac_f32_e32 v59, 0x3f317217, v56
	s_nop 1
	v_mov_b32_e32 v56, v59
	v_sub_f32_e32 v56, v58, v56
	v_mul_f32_e32 v56, 0x3d800000, v56
	ds_write_b32 v88, v56 offset:9920
	v_min_f32_e32 v56, 0, v57
	v_mul_f32_e64 v57, |v57|, s7
	v_exp_f32_e32 v57, v57
	v_mov_b32_e32 v59, 0
	v_add_f32_e32 v57, 1.0, v57
	s_nop 1
	v_log_f32_e32 v57, v57
	s_nop 0
	v_mul_f32_e32 v58, 0x3f317217, v57
	v_fma_f32 v58, v57, s8, -v58
	v_fmac_f32_e32 v58, 0x3377d1cf, v57
	v_fmac_f32_e32 v58, 0x3f317217, v57
	s_nop 1
	v_mov_b32_e32 v57, v58
	v_sub_f32_e32 v56, v56, v57
	s_movk_i32 s4, 0x100
	v_mul_f32_e32 v56, 0x3d800000, v56
	v_cmp_gt_u32_e32 vcc, s4, v125
	s_add_i32 s4, 0, 0x2000
	s_add_i32 s5, 0, 0xa000
	ds_write_b32 v88, v56 offset:42688
	v_mov_b32_e32 v56, s5
	v_mov_b32_e32 v57, s4
	v_cndmask_b32_e32 v56, v56, v57, vcc
	v_lshlrev_b32_e32 v57, 5, v113
	v_and_b32_e32 v58, 32, v57
	v_lshl_add_u32 v56, v110, 2, v56
	v_or_b32_e32 v57, 7, v58
	v_sub_u32_e32 v58, 0, v58
	s_waitcnt lgkmcnt(0)
	s_barrier

.LBB0_128:
	v_mov_b32_e32 v46, v220
	s_lshl_b32 s4, s6, 4
	v_ashrrev_i32_e32 v44, 6, v46
	s_lshl_b32 s5, s6, 6
	s_and_b32 s4, s4, 0xffffe000
	s_and_b32 s5, s5, 0x1fc0
	v_lshlrev_b32_e32 v8, 4, v44
	v_and_b32_e32 v45, 15, v46
	s_or_b32 s9, s4, s5
	v_and_b32_e32 v87, 48, v8
	v_or3_b32 v2, v45, s9, v87
	s_waitcnt lgkmcnt(0)
	v_mov_b64_e32 v[0:1], s[64:65]
	v_mad_i64_i32 v[0:1], s[4:5], v2, s96, v[0:1]
	s_bfe_u32 s7, s6, 0x20007
	s_mov_b64 s[4:5], 0x2800
	v_lshl_add_u64 v[0:1], v[0:1], 0, s[4:5]
	s_lshl_b32 s4, s7, 7
	v_and_b32_e32 v42, 0xffffffc0, v8
	v_or_b32_e32 v8, s2, v45
	v_ashrrev_i32_e32 v43, 31, v42
	v_or_b32_e32 v8, s4, v8
	v_mov_b32_e32 v9, s3
	v_lshl_add_u64 v[8:9], v[8:9], 0, v[42:43]
	v_readlane_b32 s10, v253, 10
	v_bfe_u32 v86, v46, 4, 2
	v_lshlrev_b64 v[8:9], 6, v[8:9]
	v_readlane_b32 s11, v253, 11
	v_lshlrev_b32_e32 v176, 4, v86
	s_or_b32 s4, s4, s8
	v_lshl_add_u64 v[8:9], s[10:11], 0, v[8:9]
	v_lshl_add_u64 v[8:9], v[8:9], 0, v[176:177]
	v_or_b32_e32 v10, s4, v45
	s_mov_b32 s4, 0x8000
	v_add_u32_e32 v10, v10, v42
	v_add_co_u32_e32 v40, vcc, s4, v8
	v_lshl_add_u64 v[2:3], v[0:1], 0, v[176:177]
	s_nop 0
	v_addc_co_u32_e32 v41, vcc, 0, v9, vcc
	v_ashrrev_i32_e32 v11, 31, v10
	v_readlane_b32 s12, v254, 0
	global_load_dwordx4 v[4:7], v[2:3], off
	global_load_dwordx4 v[32:35], v[40:41], off
	v_xor_b32_e32 v2, 32, v176
	v_mov_b32_e32 v3, v177
	v_lshlrev_b64 v[10:11], 2, v[10:11]
	v_readlane_b32 s22, v254, 10
	v_readlane_b32 s23, v254, 11
	v_readlane_b32 s26, v254, 14
	v_readlane_b32 s27, v254, 15
	s_mul_hi_i32 s5, s9, 0x2a00
	s_mulk_i32 s9, 0x2a00
	v_lshl_add_u64 v[0:1], v[0:1], 0, v[2:3]
	v_lshl_add_u64 v[48:49], s[22:23], 0, v[10:11]
	v_lshl_add_u64 v[50:51], s[26:27], 0, v[10:11]
	v_mov_b32_e32 v43, v220
	s_add_u32 s4, s64, s9
	global_load_dwordx4 v[0:3], v[0:1], off
	s_addc_u32 s5, s65, s5
	global_load_dwordx4 v[36:39], v[8:9], off
	global_load_dword v85, v[48:49], off
	global_load_dword v84, v[50:51], off
	global_load_dwordx4 v[28:31], v[8:9], off offset:1024
	global_load_dwordx4 v[24:27], v[40:41], off offset:1024
	global_load_dword v83, v[48:49], off offset:64
	global_load_dword v82, v[50:51], off offset:64
	global_load_dwordx4 v[20:23], v[8:9], off offset:2048
	global_load_dwordx4 v[16:19], v[40:41], off offset:2048
	global_load_dword v81, v[48:49], off offset:128
	global_load_dword v80, v[50:51], off offset:128
	global_load_dwordx4 v[12:15], v[8:9], off offset:3072
	s_nop 0
	global_load_dwordx4 v[8:11], v[40:41], off offset:3072
	global_load_dword v79, v[48:49], off offset:192
	global_load_dword v78, v[50:51], off offset:192
	s_lshl_b32 s10, s7, 8
	s_lshl_b32 s7, s7, 9
	v_readlane_b32 s13, v254, 1
	s_add_u32 s12, s4, s7
	v_lshlrev_b32_sdwa v40, v223, v43 dst_sel:DWORD dst_unused:UNUSED_PAD src0_sel:DWORD src1_sel:BYTE_0
	v_ashrrev_i32_e32 v43, 5, v43
	s_addc_u32 s13, s5, 0
	v_mov_b32_e32 v41, v177
	v_and_b32_e32 v47, -8, v43
	v_lshl_add_u64 v[40:41], s[12:13], 0, v[40:41]
	v_add_u32_e32 v50, 50, v47
	v_mad_i64_i32 v[48:49], s[12:13], v47, s96, v[40:41]
	v_mad_i64_i32 v[50:51], s[12:13], v50, s96, v[40:41]
	global_load_ushort v56, v[48:49], off offset:2048
	global_load_ushort v91, v[50:51], off offset:2048
	v_or_b32_e32 v48, 1, v47
	v_add_u32_e32 v52, 52, v47
	v_mad_i64_i32 v[48:49], s[12:13], v48, s96, v[40:41]
	v_mad_i64_i32 v[52:53], s[12:13], v52, s96, v[40:41]
	global_load_ushort v57, v[48:49], off offset:2048
	global_load_ushort v92, v[52:53], off offset:2048
	v_or_b32_e32 v48, 2, v47
	v_add_u32_e32 v54, 54, v47
	v_mad_i64_i32 v[48:49], s[12:13], v48, s96, v[40:41]
	v_mad_i64_i32 v[54:55], s[12:13], v54, s96, v[40:41]
	global_load_ushort v58, v[48:49], off offset:2048
	global_load_ushort v93, v[54:55], off offset:2048
	v_or_b32_e32 v48, 3, v47
	v_mad_i64_i32 v[48:49], s[12:13], v48, s96, v[40:41]
	global_load_ushort v59, v[48:49], off offset:2048
	v_or_b32_e32 v48, 4, v47
	v_mad_i64_i32 v[48:49], s[12:13], v48, s96, v[40:41]
	global_load_ushort v61, v[48:49], off offset:2048
	v_or_b32_e32 v48, 5, v47
	v_mad_i64_i32 v[48:49], s[12:13], v48, s96, v[40:41]
	global_load_ushort v62, v[48:49], off offset:2048
	v_or_b32_e32 v48, 6, v47
	v_mad_i64_i32 v[48:49], s[12:13], v48, s96, v[40:41]
	v_or_b32_e32 v43, 7, v43
	global_load_ushort v63, v[48:49], off offset:2048
	v_mad_i64_i32 v[48:49], s[12:13], v43, s96, v[40:41]
	global_load_ushort v43, v[48:49], off offset:2048
	v_add_u32_e32 v48, 16, v47
	v_mad_i64_i32 v[48:49], s[12:13], v48, s96, v[40:41]
	global_load_ushort v64, v[48:49], off offset:2048
	v_add_u32_e32 v48, 17, v47
	v_mad_i64_i32 v[48:49], s[12:13], v48, s96, v[40:41]
	global_load_ushort v65, v[48:49], off offset:2048
	v_add_u32_e32 v48, 18, v47
	v_mad_i64_i32 v[48:49], s[12:13], v48, s96, v[40:41]
	global_load_ushort v66, v[48:49], off offset:2048
	v_add_u32_e32 v48, 19, v47
	v_mad_i64_i32 v[48:49], s[12:13], v48, s96, v[40:41]
	global_load_ushort v67, v[48:49], off offset:2048
	v_add_u32_e32 v48, 20, v47
	v_mad_i64_i32 v[48:49], s[12:13], v48, s96, v[40:41]
	global_load_ushort v68, v[48:49], off offset:2048
	v_add_u32_e32 v48, 21, v47
	v_mad_i64_i32 v[48:49], s[12:13], v48, s96, v[40:41]
	global_load_ushort v69, v[48:49], off offset:2048
	v_add_u32_e32 v48, 22, v47
	v_mad_i64_i32 v[48:49], s[12:13], v48, s96, v[40:41]
	global_load_ushort v70, v[48:49], off offset:2048
	v_add_u32_e32 v48, 23, v47
	v_mad_i64_i32 v[48:49], s[12:13], v48, s96, v[40:41]
	global_load_ushort v71, v[48:49], off offset:2048
	v_add_u32_e32 v48, 32, v47
	v_mad_i64_i32 v[48:49], s[12:13], v48, s96, v[40:41]
	global_load_ushort v72, v[48:49], off offset:2048
	v_add_u32_e32 v48, 33, v47
	v_mad_i64_i32 v[48:49], s[12:13], v48, s96, v[40:41]
	global_load_ushort v73, v[48:49], off offset:2048
	v_add_u32_e32 v48, 34, v47
	v_mad_i64_i32 v[48:49], s[12:13], v48, s96, v[40:41]
	global_load_ushort v74, v[48:49], off offset:2048
	v_add_u32_e32 v48, 35, v47
	v_mad_i64_i32 v[48:49], s[12:13], v48, s96, v[40:41]
	global_load_ushort v75, v[48:49], off offset:2048
	v_add_u32_e32 v48, 36, v47
	v_mad_i64_i32 v[48:49], s[12:13], v48, s96, v[40:41]
	global_load_ushort v76, v[48:49], off offset:2048
	v_add_u32_e32 v48, 37, v47
	v_mad_i64_i32 v[48:49], s[12:13], v48, s96, v[40:41]
	global_load_ushort v77, v[48:49], off offset:2048
	v_add_u32_e32 v48, 38, v47
	v_mad_i64_i32 v[48:49], s[12:13], v48, s96, v[40:41]
	global_load_ushort v88, v[48:49], off offset:2048
	v_add_u32_e32 v48, 39, v47
	v_mad_i64_i32 v[48:49], s[12:13], v48, s96, v[40:41]
	global_load_ushort v89, v[48:49], off offset:2048
	v_add_u32_e32 v48, 48, v47
	v_mad_i64_i32 v[48:49], s[12:13], v48, s96, v[40:41]
	global_load_ushort v90, v[48:49], off offset:2048
	v_add_u32_e32 v48, 49, v47
	v_add_u32_e32 v50, 51, v47
	v_add_u32_e32 v52, 53, v47
	v_add_u32_e32 v47, 55, v47
	v_mad_i64_i32 v[48:49], s[12:13], v48, s96, v[40:41]
	v_mad_i64_i32 v[50:51], s[12:13], v50, s96, v[40:41]
	v_mad_i64_i32 v[52:53], s[12:13], v52, s96, v[40:41]
	v_mad_i64_i32 v[40:41], s[12:13], v47, s96, v[40:41]
	global_load_ushort v41, v[40:41], off offset:2048
	s_nop 0
	global_load_ushort v47, v[52:53], off offset:2048
	global_load_ushort v94, v[50:51], off offset:2048
	global_load_ushort v95, v[48:49], off offset:2048
	s_mov_b32 s9, 0x5040100
	s_waitcnt vmcnt(0)
	v_perm_b32 v51, v43, v63, s9
	s_waitcnt lgkmcnt(0)
	s_barrier
	v_perm_b32 v50, v62, v61, s9
	v_perm_b32 v52, v65, v64, s9
	v_perm_b32 v49, v59, v58, s9
	v_perm_b32 v48, v57, v56, s9
	v_and_b32_e32 v40, 0x7f, v46
	v_ashrrev_i32_e32 v60, 7, v46
	v_mfma_f32_16x16x32_bf16 v[36:39], v[4:7], v[36:39], 0
	s_mov_b32 s11, 0x3f317217
	v_or_b32_e32 v42, v42, v45
	v_perm_b32 v53, v67, v66, s9
	v_mfma_f32_16x16x32_bf16 v[32:35], v[0:3], v[32:35], 0
	v_readlane_b32 s14, v254, 2
	s_nop 2
	v_add_f32_e32 v37, v85, v37
	v_add_f32_e32 v38, v85, v38
	v_add_f32_e32 v39, v85, v39
	v_mfma_f32_16x16x32_bf16 v[28:31], v[4:7], v[28:31], 0
	v_add_f32_e32 v33, v84, v33
	v_perm_b32 v54, v69, v68, s9
	s_mov_b32 s7, 32
	v_mfma_f32_16x16x32_bf16 v[24:27], v[0:3], v[24:27], 0
	s_movk_i32 s14, 0x90
	s_nop 2
	v_add_f32_e32 v28, v83, v28
	v_add_f32_e32 v29, v83, v29
	v_add_f32_e32 v31, v83, v31
	v_mfma_f32_16x16x32_bf16 v[20:23], v[4:7], v[20:23], 0
	v_perm_b32 v55, v71, v70, s9
	v_add_f32_e32 v25, v82, v25
	v_add_f32_e32 v26, v82, v26
	v_mfma_f32_16x16x32_bf16 v[16:19], v[0:3], v[16:19], 0
	v_readlane_b32 s15, v254, 3
	s_nop 2
	v_add_f32_e32 v20, v81, v20
	v_add_f32_e32 v21, v81, v21
	v_add_f32_e32 v22, v81, v22
	v_perm_b32 v56, v73, v72, s9
	v_add_f32_e32 v16, v80, v16
	v_mfma_f32_16x16x32_bf16 v[4:7], v[4:7], v[12:15], 0
	v_readlane_b32 s16, v254, 4
	v_readlane_b32 s17, v254, 5
	v_readlane_b32 s18, v254, 6
	v_mfma_f32_16x16x32_bf16 v[0:3], v[0:3], v[8:11], 0
	v_readlane_b32 s19, v254, 7
	v_perm_b32 v57, v75, v74, s9
	s_nop 1
	v_add_f32_e32 v4, v79, v4
	v_add_f32_e32 v5, v79, v5
	v_readlane_b32 s20, v254, 8
	s_nop 0
	v_add_f32_e32 v0, v78, v0
	v_readlane_b32 s21, v254, 9
	v_readlane_b32 s24, v254, 12
	v_readlane_b32 s25, v254, 13
	v_perm_b32 v58, v77, v76, s9
	v_perm_b32 v59, v89, v88, s9
	v_perm_b32 v65, v41, v93, s9
	v_mov_b32_e32 v41, v220
	v_perm_b32 v64, v47, v92, s9
	v_ashrrev_i32_e32 v43, 5, v41
	v_lshlrev_b32_e32 v43, 1, v43
	v_perm_b32 v63, v94, v91, s9
	v_perm_b32 v62, v95, v90, s9
	v_mul_u32_u24_sdwa v41, v41, s28 dst_sel:DWORD dst_unused:UNUSED_PAD src0_sel:BYTE_0 src1_sel:DWORD
	s_add_i32 s9, 0, 0x12000
	v_and_b32_e32 v43, -16, v43
	v_add3_u32 v41, s9, v41, v43
	s_add_u32 s4, s4, s10
	ds_write_b128 v41, v[48:51]
	ds_write_b128 v41, v[52:55] offset:32
	ds_write_b128 v41, v[56:59] offset:64
	ds_write_b128 v41, v[62:65] offset:96
	s_addc_u32 s5, s5, 0
	v_lshlrev_b32_e32 v48, 1, v40
	v_mov_b32_e32 v49, v177
	v_lshlrev_b32_e32 v50, 3, v60
	v_lshl_add_u64 v[88:89], s[4:5], 0, v[48:49]
	v_add_u32_e32 v74, 35, v50
	v_mad_i64_i32 v[48:49], s[4:5], v50, s96, v[88:89]
	v_or_b32_e32 v67, 1, v50
	v_mad_i64_i32 v[70:71], s[4:5], v74, s96, v[88:89]
	v_add_u32_e32 v73, 36, v50
	global_load_ushort v68, v[48:49], off offset:1024
	global_load_ushort v51, v[70:71], off offset:1024
	v_mad_i64_i32 v[48:49], s[4:5], v67, s96, v[88:89]
	v_or_b32_e32 v66, 2, v50
	v_mad_i64_i32 v[70:71], s[4:5], v73, s96, v[88:89]
	v_add_u32_e32 v72, 37, v50
	global_load_ushort v69, v[48:49], off offset:1024
	global_load_ushort v43, v[70:71], off offset:1024
	v_mad_i64_i32 v[48:49], s[4:5], v66, s96, v[88:89]
	v_mad_i64_i32 v[70:71], s[4:5], v72, s96, v[88:89]
	global_load_ushort v61, v[48:49], off offset:1024
	global_load_ushort v47, v[70:71], off offset:1024
	v_or_b32_e32 v65, 3, v50
	v_add_u32_e32 v71, 38, v50
	v_mad_i64_i32 v[48:49], s[4:5], v65, s96, v[88:89]
	v_or_b32_e32 v64, 4, v50
	v_mad_i64_i32 v[90:91], s[4:5], v71, s96, v[88:89]
	global_load_ushort v62, v[48:49], off offset:1024
	global_load_ushort v41, v[90:91], off offset:1024
	v_mad_i64_i32 v[48:49], s[4:5], v64, s96, v[88:89]
	v_or_b32_e32 v63, 5, v50
	global_load_ushort v55, v[48:49], off offset:1024
	v_mad_i64_i32 v[48:49], s[4:5], v63, s96, v[88:89]
	v_or_b32_e32 v59, 6, v50
	global_load_ushort v56, v[48:49], off offset:1024
	v_mad_i64_i32 v[48:49], s[4:5], v59, s96, v[88:89]
	v_or_b32_e32 v57, 7, v50
	global_load_ushort v54, v[48:49], off offset:1024
	v_mad_i64_i32 v[48:49], s[4:5], v57, s96, v[88:89]
	v_add_u32_e32 v77, 32, v50
	global_load_ushort v58, v[48:49], off offset:1024
	v_mad_i64_i32 v[48:49], s[4:5], v77, s96, v[88:89]
	v_add_u32_e32 v76, 33, v50
	global_load_ushort v52, v[48:49], off offset:1024
	v_mad_i64_i32 v[48:49], s[4:5], v76, s96, v[88:89]
	v_add_u32_e32 v75, 34, v50
	v_add_u32_e32 v70, 39, v50
	global_load_ushort v53, v[48:49], off offset:1024
	v_mad_i64_i32 v[48:49], s[4:5], v75, s96, v[88:89]
	v_mad_i64_i32 v[88:89], s[4:5], v70, s96, v[88:89]
	global_load_ushort v49, v[48:49], off offset:1024
	s_mov_b32 s10, 0xbfb8aa3b
	global_load_ushort v48, v[88:89], off offset:1024
	v_add_f32_e32 v88, v85, v36
	v_mul_f32_e64 v36, |v88|, s10
	v_exp_f32_e32 v89, v36
	v_lshlrev_b32_e32 v36, 2, v86
	v_or_b32_e32 v86, v36, v87
	v_mul_f32_e64 v85, |v39|, s10
	v_add_f32_e32 v87, 1.0, v89
	v_exp_f32_e32 v85, v85
	v_mul_f32_e64 v12, |v4|, s10
	v_log_f32_e32 v87, v87
	v_add_f32_e32 v89, v84, v32
	v_min_f32_e32 v32, 0, v88
	v_mul_f32_e64 v90, |v89|, s10
	v_mul_f32_e32 v88, 0x3f317217, v87
	v_fma_f32 v88, v87, s11, -v88
	v_fmac_f32_e32 v88, 0x3377d1cf, v87
	v_fmac_f32_e32 v88, 0x3f317217, v87
	v_exp_f32_e32 v90, v90
	v_exp_f32_e32 v12, v12
	v_mov_b32_e32 v87, v88
	v_sub_f32_e32 v32, v32, v87
	v_mul_f32_e32 v87, 0x3d800000, v32
	v_add_f32_e32 v32, 1.0, v90
	v_add_f32_e32 v12, 1.0, v12
	v_mul_f32_e64 v9, |v0|, s10
	v_log_f32_e32 v88, v32
	v_lshl_add_u32 v32, v86, 7, v42
	v_min_f32_e32 v42, 0, v89
	v_mul_f32_e32 v86, 0x3f317217, v88
	v_fma_f32 v86, v88, s11, -v86
	v_fmac_f32_e32 v86, 0x3377d1cf, v88
	v_fmac_f32_e32 v86, 0x3f317217, v88
	v_lshl_add_u32 v32, v32, 2, 0
	v_exp_f32_e32 v9, v9
	v_mul_f32_e64 v88, |v37|, s10
	v_exp_f32_e32 v88, v88
	v_sub_f32_e32 v42, v42, v86
	v_mul_f32_e64 v89, |v33|, s10
	v_add_f32_e32 v86, 1.0, v88
	v_exp_f32_e32 v89, v89
	v_min_f32_e32 v37, 0, v37
	v_log_f32_e32 v86, v86
	v_min_f32_e32 v33, 0, v33
	v_mul_f32_e32 v42, 0x3d800000, v42
	v_min_f32_e32 v4, 0, v4
	v_mul_f32_e32 v88, 0x3f317217, v86
	v_fma_f32 v88, v86, s11, -v88
	v_fmac_f32_e32 v88, 0x3377d1cf, v86
	v_fmac_f32_e32 v88, 0x3f317217, v86
	v_min_f32_e32 v0, 0, v0
	s_nop 0
	v_mov_b32_e32 v86, v88
	v_add_f32_e32 v88, 1.0, v89
	v_sub_f32_e32 v37, v37, v86
	v_mul_f32_e32 v37, 0x3d800000, v37
	v_log_f32_e32 v88, v88
	v_mul_f32_e64 v89, |v38|, s10
	v_exp_f32_e32 v89, v89
	v_mul_f32_e32 v86, 0x3f317217, v88
	v_fma_f32 v86, v88, s11, -v86
	v_fmac_f32_e32 v86, 0x3377d1cf, v88
	v_fmac_f32_e32 v86, 0x3f317217, v88
	s_nop 1
	v_sub_f32_e32 v33, v33, v86
	v_add_f32_e32 v86, 1.0, v89
	v_mul_f32_e32 v33, 0x3d800000, v33
	ds_write_b32 v32, v33 offset:41472
	v_log_f32_e32 v86, v86
	v_add_f32_e32 v33, v84, v34
	v_min_f32_e32 v34, 0, v38
	v_mul_f32_e32 v38, 0x3f317217, v86
	v_fma_f32 v38, v86, s11, -v38
	v_fmac_f32_e32 v38, 0x3377d1cf, v86
	v_fmac_f32_e32 v38, 0x3f317217, v86
	s_nop 1
	v_mul_f32_e64 v86, |v33|, s10
	v_exp_f32_e32 v86, v86
	v_sub_f32_e32 v34, v34, v38
	v_mul_f32_e32 v34, 0x3d800000, v34
	v_add_f32_e32 v38, 1.0, v86
	ds_write_b32 v32, v34 offset:9216
	v_min_f32_e32 v33, 0, v33
	v_log_f32_e32 v38, v38
	s_nop 0
	v_mul_f32_e32 v34, 0x3f317217, v38
	v_fma_f32 v34, v38, s11, -v34
	v_fmac_f32_e32 v34, 0x3377d1cf, v38
	v_fmac_f32_e32 v34, 0x3f317217, v38
	s_nop 1
	v_sub_f32_e32 v33, v33, v34
	v_add_f32_e32 v34, 1.0, v85
	v_mul_f32_e32 v33, 0x3d800000, v33
	ds_write_b32 v32, v33 offset:41984
	v_log_f32_e32 v34, v34
	v_add_f32_e32 v33, v84, v35
	v_min_f32_e32 v35, 0, v39
	v_mul_f32_e32 v38, 0x3f317217, v34
	v_fma_f32 v38, v34, s11, -v38
	v_fmac_f32_e32 v38, 0x3377d1cf, v34
	v_fmac_f32_e32 v38, 0x3f317217, v34
	s_nop 1
	v_mov_b32_e32 v34, v38
	v_mul_f32_e64 v38, |v33|, s10
	v_exp_f32_e32 v38, v38
	v_sub_f32_e32 v34, v35, v34
	v_mul_f32_e32 v34, 0x3d800000, v34
	v_add_f32_e32 v35, 1.0, v38
	ds_write_b32 v32, v34 offset:9728
	v_min_f32_e32 v33, 0, v33
	v_log_f32_e32 v35, v35
	s_nop 0
	v_mul_f32_e32 v34, 0x3f317217, v35
	v_fma_f32 v34, v35, s11, -v34
	v_fmac_f32_e32 v34, 0x3377d1cf, v35
	v_fmac_f32_e32 v34, 0x3f317217, v35
	s_nop 1
	v_mul_f32_e64 v35, |v28|, s10
	v_exp_f32_e32 v35, v35
	v_sub_f32_e32 v33, v33, v34
	v_mul_f32_e32 v33, 0x3d800000, v33
	ds_write_b32 v32, v33 offset:42496
	v_add_f32_e32 v33, 1.0, v35
	s_nop 1
	v_log_f32_e32 v33, v33
	v_add_f32_e32 v34, v82, v24
	v_min_f32_e32 v24, 0, v28
	v_mul_f32_e64 v35, |v34|, s10
	v_mul_f32_e32 v28, 0x3f317217, v33
	v_fma_f32 v28, v33, s11, -v28
	v_fmac_f32_e32 v28, 0x3377d1cf, v33
	v_fmac_f32_e32 v28, 0x3f317217, v33
	v_exp_f32_e32 v35, v35
	s_nop 0
	v_sub_f32_e32 v24, v24, v28
	v_mul_f32_e32 v28, 0x3d800000, v24
	v_add_f32_e32 v24, 1.0, v35
	s_nop 1
	v_log_f32_e32 v33, v24
	v_add_u32_e32 v24, 0x2000, v32
	ds_write2_b32 v24, v87, v28 offset1:16
	v_min_f32_e32 v28, 0, v34
	v_mul_f32_e32 v34, 0x3f317217, v33
	v_fma_f32 v34, v33, s11, -v34
	v_fmac_f32_e32 v34, 0x3377d1cf, v33
	v_fmac_f32_e32 v34, 0x3f317217, v33
	s_nop 1
	v_mov_b32_e32 v33, v34
	v_mul_f32_e64 v34, |v29|, s10
	v_exp_f32_e32 v34, v34
	v_sub_f32_e32 v28, v28, v33
	v_mul_f32_e32 v28, 0x3d800000, v28
	v_add_u32_e32 v33, 0xa000, v32
	v_add_f32_e32 v34, 1.0, v34
	ds_write2_b32 v33, v42, v28 offset1:16
	v_min_f32_e32 v28, 0, v29
	v_log_f32_e32 v34, v34
	s_nop 0
	v_mul_f32_e32 v29, 0x3f317217, v34
	v_fma_f32 v29, v34, s11, -v29
	v_fmac_f32_e32 v29, 0x3377d1cf, v34
	v_fmac_f32_e32 v29, 0x3f317217, v34
	s_nop 1
	v_mul_f32_e64 v34, |v25|, s10
	v_exp_f32_e32 v34, v34
	v_sub_f32_e32 v28, v28, v29
	v_mul_f32_e32 v28, 0x3d800000, v28
	v_add_f32_e32 v29, 1.0, v34
	ds_write2_b32 v24, v37, v28 offset0:128 offset1:144
	v_min_f32_e32 v25, 0, v25
	v_log_f32_e32 v29, v29
	s_nop 0
	v_mul_f32_e32 v28, 0x3f317217, v29
	v_fma_f32 v28, v29, s11, -v28
	v_fmac_f32_e32 v28, 0x3377d1cf, v29
	v_fmac_f32_e32 v28, 0x3f317217, v29
	s_nop 1
	v_add_f32_e32 v29, v83, v30
	v_mul_f32_e64 v30, |v29|, s10
	v_exp_f32_e32 v30, v30
	v_sub_f32_e32 v25, v25, v28
	v_mul_f32_e64 v34, |v26|, s10
	v_add_f32_e32 v28, 1.0, v30
	v_exp_f32_e32 v34, v34
	v_min_f32_e32 v29, 0, v29
	v_log_f32_e32 v28, v28
	v_min_f32_e32 v26, 0, v26
	v_mul_f32_e32 v25, 0x3d800000, v25
	v_mul_f32_e32 v30, 0x3f317217, v28
	v_fma_f32 v30, v28, s11, -v30
	v_fmac_f32_e32 v30, 0x3377d1cf, v28
	v_fmac_f32_e32 v30, 0x3f317217, v28
	s_nop 1
	v_mov_b32_e32 v28, v30
	v_add_f32_e32 v30, 1.0, v34
	v_sub_f32_e32 v28, v29, v28
	v_mul_f32_e32 v28, 0x3d800000, v28
	v_log_f32_e32 v30, v30
	v_mul_f32_e64 v34, |v31|, s10
	v_exp_f32_e32 v34, v34
	v_mul_f32_e32 v29, 0x3f317217, v30
	v_fma_f32 v29, v30, s11, -v29
	v_fmac_f32_e32 v29, 0x3377d1cf, v30
	v_fmac_f32_e32 v29, 0x3f317217, v30
	s_nop 1
	v_sub_f32_e32 v26, v26, v29
	v_add_f32_e32 v29, 1.0, v34
	v_mul_f32_e32 v26, 0x3d800000, v26
	ds_write_b32 v32, v26 offset:42048
	v_log_f32_e32 v29, v29
	v_add_f32_e32 v26, v82, v27
	v_min_f32_e32 v27, 0, v31
	v_mul_f32_e32 v30, 0x3f317217, v29
	v_fma_f32 v30, v29, s11, -v30
	v_fmac_f32_e32 v30, 0x3377d1cf, v29
	v_fmac_f32_e32 v30, 0x3f317217, v29
	s_nop 1
	v_mov_b32_e32 v29, v30
	v_mul_f32_e64 v30, |v26|, s10
	v_exp_f32_e32 v30, v30
	v_sub_f32_e32 v27, v27, v29
	v_mul_f32_e32 v27, 0x3d800000, v27
	v_add_f32_e32 v29, 1.0, v30
	ds_write_b32 v32, v27 offset:9792
	v_min_f32_e32 v26, 0, v26
	v_log_f32_e32 v29, v29
	s_nop 0
	v_mul_f32_e32 v27, 0x3f317217, v29
	v_fma_f32 v27, v29, s11, -v27
	v_fmac_f32_e32 v27, 0x3377d1cf, v29
	v_fmac_f32_e32 v27, 0x3f317217, v29
	s_nop 1
	v_mul_f32_e64 v29, |v20|, s10
	v_exp_f32_e32 v29, v29
	v_sub_f32_e32 v26, v26, v27
	v_mul_f32_e32 v26, 0x3d800000, v26
	ds_write_b32 v32, v26 offset:42560
	v_add_f32_e32 v26, 1.0, v29
	v_mul_f32_e64 v29, |v16|, s10
	v_exp_f32_e32 v29, v29
	v_log_f32_e32 v26, v26
	v_min_f32_e32 v20, 0, v20
	v_min_f32_e32 v16, 0, v16
	v_mul_f32_e32 v27, 0x3f317217, v26
	v_fma_f32 v27, v26, s11, -v27
	v_fmac_f32_e32 v27, 0x3377d1cf, v26
	v_fmac_f32_e32 v27, 0x3f317217, v26
	s_nop 1
	v_mov_b32_e32 v26, v27
	v_add_f32_e32 v27, 1.0, v29
	v_sub_f32_e32 v20, v20, v26
	v_mul_f32_e32 v20, 0x3d800000, v20
	v_log_f32_e32 v27, v27
	v_mul_f32_e64 v29, |v21|, s10
	v_exp_f32_e32 v29, v29
	v_mul_f32_e32 v26, 0x3f317217, v27
	v_fma_f32 v26, v27, s11, -v26
	v_fmac_f32_e32 v26, 0x3377d1cf, v27
	v_fmac_f32_e32 v26, 0x3f317217, v27
	s_nop 1
	v_sub_f32_e32 v16, v16, v26
	v_add_f32_e32 v26, 1.0, v29
	v_mul_f32_e32 v16, 0x3d800000, v16
	ds_write_b32 v32, v16 offset:41088
	v_log_f32_e32 v26, v26
	v_add_f32_e32 v16, v80, v17
	v_min_f32_e32 v17, 0, v21
	v_mul_f32_e32 v21, 0x3f317217, v26
	v_fma_f32 v21, v26, s11, -v21
	v_fmac_f32_e32 v21, 0x3377d1cf, v26
	v_fmac_f32_e32 v21, 0x3f317217, v26
	s_nop 1
	v_mul_f32_e64 v26, |v16|, s10
	v_exp_f32_e32 v26, v26
	v_sub_f32_e32 v17, v17, v21
	v_mul_f32_e32 v17, 0x3d800000, v17
	v_add_f32_e32 v21, 1.0, v26
	ds_write_b32 v32, v17 offset:8832
	v_min_f32_e32 v16, 0, v16
	v_log_f32_e32 v21, v21
	v_mul_f32_e64 v26, |v22|, s10
	v_exp_f32_e32 v26, v26
	v_mul_f32_e32 v17, 0x3f317217, v21
	v_fma_f32 v17, v21, s11, -v17
	v_fmac_f32_e32 v17, 0x3377d1cf, v21
	v_fmac_f32_e32 v17, 0x3f317217, v21
	s_nop 1
	v_sub_f32_e32 v16, v16, v17
	v_add_f32_e32 v17, 1.0, v26
	v_mul_f32_e32 v16, 0x3d800000, v16
	ds_write2_b32 v33, v25, v16 offset0:144 offset1:160
	v_log_f32_e32 v17, v17
	v_add_f32_e32 v16, v80, v18
	v_min_f32_e32 v18, 0, v22
	v_mul_f32_e64 v22, |v16|, s10
	v_mul_f32_e32 v21, 0x3f317217, v17
	v_fma_f32 v21, v17, s11, -v21
	v_fmac_f32_e32 v21, 0x3377d1cf, v17
	v_exp_f32_e32 v22, v22
	v_fmac_f32_e32 v21, 0x3f317217, v17
	v_min_f32_e32 v16, 0, v16
	s_nop 0
	v_mov_b32_e32 v17, v21
	v_sub_f32_e32 v17, v18, v17
	v_add_f32_e32 v18, 1.0, v22
	v_mul_f32_e32 v17, 0x3d800000, v17
	s_nop 0
	v_log_f32_e32 v18, v18
	v_add_u32_e32 v21, 0x2400, v32
	ds_write2_b32 v21, v28, v17 offset0:16 offset1:32
	v_add_f32_e32 v21, v81, v23
	v_mul_f32_e32 v17, 0x3f317217, v18
	v_fma_f32 v17, v18, s11, -v17
	v_mul_f32_e64 v22, |v21|, s10
	v_fmac_f32_e32 v17, 0x3377d1cf, v18
	v_exp_f32_e32 v22, v22
	v_fmac_f32_e32 v17, 0x3f317217, v18
	s_nop 1
	v_sub_f32_e32 v16, v16, v17
	v_add_f32_e32 v17, 1.0, v22
	v_mul_f32_e32 v16, 0x3d800000, v16
	ds_write_b32 v32, v16 offset:42112
	v_log_f32_e32 v17, v17
	v_add_f32_e32 v16, v80, v19
	v_min_f32_e32 v18, 0, v21
	v_mul_f32_e32 v19, 0x3f317217, v17
	v_fma_f32 v19, v17, s11, -v19
	v_fmac_f32_e32 v19, 0x3377d1cf, v17
	v_fmac_f32_e32 v19, 0x3f317217, v17
	s_nop 1
	v_mov_b32_e32 v17, v19
	v_mul_f32_e64 v19, |v16|, s10
	v_exp_f32_e32 v19, v19
	v_sub_f32_e32 v17, v18, v17
	v_mul_f32_e32 v17, 0x3d800000, v17
	v_add_f32_e32 v18, 1.0, v19
	ds_write_b32 v32, v17 offset:9856
	v_min_f32_e32 v16, 0, v16
	v_log_f32_e32 v18, v18
	s_nop 0
	v_mul_f32_e32 v17, 0x3f317217, v18
	v_fma_f32 v17, v18, s11, -v17
	v_fmac_f32_e32 v17, 0x3377d1cf, v18
	v_fmac_f32_e32 v17, 0x3f317217, v18
	s_nop 1
	v_sub_f32_e32 v13, v16, v17
	v_mul_f32_e32 v13, 0x3d800000, v13
	ds_write_b32 v32, v13 offset:42624
	s_nop 0
	v_log_f32_e32 v12, v12
	s_nop 0
	v_mul_f32_e32 v8, 0x3f317217, v12
	v_fma_f32 v8, v12, s11, -v8
	v_fmac_f32_e32 v8, 0x3377d1cf, v12
	v_fmac_f32_e32 v8, 0x3f317217, v12
	s_nop 1
	v_sub_f32_e32 v4, v4, v8
	v_add_f32_e32 v8, 1.0, v9
	v_mul_f32_e32 v4, 0x3d800000, v4
	ds_write2_b32 v24, v20, v4 offset0:32 offset1:48
	v_log_f32_e32 v8, v8
	v_mul_f32_e64 v9, |v5|, s10
	v_exp_f32_e32 v9, v9
	v_mul_f32_e32 v4, 0x3f317217, v8
	v_fma_f32 v4, v8, s11, -v4
	v_fmac_f32_e32 v4, 0x3377d1cf, v8
	v_fmac_f32_e32 v4, 0x3f317217, v8
	s_nop 1
	v_sub_f32_e32 v0, v0, v4
	v_add_f32_e32 v4, 1.0, v9
	v_mul_f32_e32 v0, 0x3d800000, v0
	ds_write_b32 v32, v0 offset:41152
	v_log_f32_e32 v4, v4
	v_add_f32_e32 v0, v78, v1
	v_min_f32_e32 v1, 0, v5
	v_mul_f32_e32 v5, 0x3f317217, v4
	v_fma_f32 v5, v4, s11, -v5
	v_fmac_f32_e32 v5, 0x3377d1cf, v4
	v_fmac_f32_e32 v5, 0x3f317217, v4
	s_nop 1
	v_mov_b32_e32 v4, v5
	v_mul_f32_e64 v5, |v0|, s10
	v_exp_f32_e32 v5, v5
	v_sub_f32_e32 v1, v1, v4
	v_mul_f32_e32 v1, 0x3d800000, v1
	v_add_f32_e32 v4, 1.0, v5
	ds_write_b32 v32, v1 offset:8896
	v_min_f32_e32 v0, 0, v0
	v_log_f32_e32 v4, v4
	v_add_f32_e32 v5, v79, v6
	v_mul_f32_e64 v6, |v5|, s10
	v_exp_f32_e32 v6, v6
	v_mul_f32_e32 v1, 0x3f317217, v4
	v_fma_f32 v1, v4, s11, -v1
	v_fmac_f32_e32 v1, 0x3377d1cf, v4
	v_fmac_f32_e32 v1, 0x3f317217, v4
	s_nop 1
	v_sub_f32_e32 v0, v0, v1
	v_add_f32_e32 v1, 1.0, v6
	v_mul_f32_e32 v0, 0x3d800000, v0
	ds_write_b32 v32, v0 offset:41664
	v_log_f32_e32 v1, v1
	v_add_f32_e32 v0, v78, v2
	v_min_f32_e32 v2, 0, v5
	v_mul_f32_e32 v4, 0x3f317217, v1
	v_fma_f32 v4, v1, s11, -v4
	v_fmac_f32_e32 v4, 0x3377d1cf, v1
	v_fmac_f32_e32 v4, 0x3f317217, v1
	s_nop 1
	v_mov_b32_e32 v1, v4
	v_mul_f32_e64 v4, |v0|, s10
	v_exp_f32_e32 v4, v4
	v_sub_f32_e32 v1, v2, v1
	v_mul_f32_e32 v1, 0x3d800000, v1
	v_add_f32_e32 v2, 1.0, v4
	ds_write_b32 v32, v1 offset:9408
	v_min_f32_e32 v0, 0, v0
	v_log_f32_e32 v2, v2
	v_add_f32_e32 v4, v79, v7
	v_mul_f32_e64 v5, |v4|, s10
	v_exp_f32_e32 v5, v5
	v_mul_f32_e32 v1, 0x3f317217, v2
	v_fma_f32 v1, v2, s11, -v1
	v_fmac_f32_e32 v1, 0x3377d1cf, v2
	v_fmac_f32_e32 v1, 0x3f317217, v2
	s_nop 1
	v_sub_f32_e32 v0, v0, v1
	v_add_f32_e32 v1, 1.0, v5
	v_mul_f32_e32 v0, 0x3d800000, v0
	ds_write_b32 v32, v0 offset:42176
	v_log_f32_e32 v1, v1
	v_add_f32_e32 v0, v78, v3
	v_min_f32_e32 v2, 0, v4
	v_mul_f32_e32 v3, 0x3f317217, v1
	v_fma_f32 v3, v1, s11, -v3
	v_fmac_f32_e32 v3, 0x3377d1cf, v1
	v_fmac_f32_e32 v3, 0x3f317217, v1
	s_nop 1
	v_mov_b32_e32 v1, v3
	v_mul_f32_e64 v3, |v0|, s10
	v_exp_f32_e32 v3, v3
	v_sub_f32_e32 v1, v2, v1
	v_mul_f32_e32 v1, 0x3d800000, v1
	v_add_f32_e32 v2, 1.0, v3
	ds_write_b32 v32, v1 offset:9920
	v_min_f32_e32 v0, 0, v0
	v_log_f32_e32 v2, v2
	v_mov_b32_e32 v3, 0
	v_mul_f32_e32 v1, 0x3f317217, v2
	v_fma_f32 v1, v2, s11, -v1
	v_fmac_f32_e32 v1, 0x3377d1cf, v2
	v_fmac_f32_e32 v1, 0x3f317217, v2
	s_nop 1
	v_sub_f32_e32 v0, v0, v1
	s_movk_i32 s4, 0x100
	v_mul_f32_e32 v0, 0x3d800000, v0
	v_cmp_gt_u32_e32 vcc, s4, v46
	s_add_i32 s4, 0, 0x2000
	s_add_i32 s5, 0, 0xa000
	ds_write_b32 v32, v0 offset:42688
	v_mov_b32_e32 v0, s5
	v_mov_b32_e32 v1, s4
	v_cndmask_b32_e32 v0, v0, v1, vcc
	v_lshlrev_b32_e32 v1, 5, v60
	v_and_b32_e32 v2, 32, v1
	v_lshl_add_u32 v0, v40, 2, v0
	v_or_b32_e32 v1, 7, v2
	v_sub_u32_e32 v2, 0, v2
	s_waitcnt lgkmcnt(0)
	s_barrier
